# v117 plus v_mov_b64 accumulator init in the MLA loops, NA queue ticket lookahead, NA K/V descriptor kept in SGPRs across a unit's pieces
# speedup vs baseline: 1.0075x; 1.0075x over previous
.LBB0_728:
	s_mul_i32 s1, s18, 0x6400
	s_cmp_eq_u32 s20, 0
	s_cselect_b64 s[8:9], -1, 0
	s_add_i32 s1, s21, s10
	s_mov_b32 m0, s1
	v_xor_b32_e32 v96, 0x80000000, v208
	v_mov_b32_e32 v97, v96
	buffer_load_dwordx4 v129, s[24:27], s0 offen lds
	v_mov_b64_e32 v[98:99], v[96:97]
	v_mov_b64_e32 v[100:101], v[96:97]
	v_mov_b64_e32 v[102:103], v[96:97]
	v_mov_b64_e32 v[104:105], v[96:97]
	v_mov_b64_e32 v[106:107], v[96:97]
	v_mov_b64_e32 v[108:109], v[96:97]
	v_mov_b64_e32 v[110:111], v[96:97]
	v_max_f32_e32 v130, v81, v81
	s_waitcnt lgkmcnt(2)
	v_mfma_f32_32x32x16_bf16 v[112:127], v[244:247], v[136:139], v[96:111]
	v_max_f32_e32 v184, v80, v80
	v_max_f32_e32 v130, v184, v130
	v_max3_f32 v130, v130, v82, v83
	v_max3_f32 v130, v130, v84, v85
	v_max3_f32 v130, v130, v86, v87
	s_add_i32 m0, s1, 0x2000
	ds_read_b128 v[184:187], v212 offset:96
	buffer_load_dwordx4 v131, s[24:27], s0 offen lds
	s_waitcnt lgkmcnt(2)
	v_mfma_f32_32x32x16_bf16 v[112:127], v[248:251], v[140:143], v[112:127]
	v_max3_f32 v130, v130, v88, v89
	v_max3_f32 v130, v130, v90, v91
	v_max3_f32 v130, v130, v92, v93
	v_max3_f32 v130, v130, v94, v95
	s_add_i32 m0, s1, 0x4000
	ds_read_b128 v[234:237], v212 offset:128
	buffer_load_dwordx4 v199, s[24:27], s0 offen lds
	s_waitcnt lgkmcnt(2)
	v_mfma_f32_32x32x16_bf16 v[112:127], v[230:233], v[144:147], v[112:127]
	v_max3_f32 v130, v130, v64, v65
	v_max3_f32 v130, v130, v66, v67
	v_max3_f32 v130, v130, v68, v69
	v_max3_f32 v130, v130, v70, v71
	s_add_i32 s23, s23, s10
	s_mov_b32 s14, s26
	s_mov_b32 s15, s27
	s_mov_b32 m0, s23
	ds_read_b128 v[188:191], v212 offset:160
	buffer_load_dwordx4 v203, s[12:15], s22 offen lds
	s_waitcnt lgkmcnt(2)
	v_mfma_f32_32x32x16_bf16 v[112:127], v[184:187], v[148:151], v[112:127]
	v_max3_f32 v130, v130, v72, v73
	v_max3_f32 v130, v130, v74, v75
	v_max3_f32 v130, v130, v76, v77
	v_max3_f32 v130, v130, v78, v79
	v_mov_b32_e32 v192, v130
	s_waitcnt lgkmcnt(1)
	v_mfma_f32_32x32x16_bf16 v[112:127], v[234:237], v[152:155], v[112:127]
	v_permlane32_swap_b32_e32 v130, v192
	v_max_f32_e32 v192, v192, v192
	v_max_f32_e32 v130, v130, v130
	v_max_f32_e32 v130, v130, v192
	ds_read_b128 v[184:187], v212 offset:192
	v_cmp_lt_f32_e32 vcc, s68, v130
	s_cmp_lg_u64 vcc, 0
	s_cselect_b64 s[0:1], -1, 0
	s_or_b64 s[0:1], s[8:9], s[0:1]
	s_and_b64 vcc, exec, s[0:1]
	s_cbranch_vccz .LBB0_730
	v_max_f32_e32 v192, v130, v130
	v_max_f32_e32 v192, 0, v192
	v_cndmask_b32_e64 v130, v192, v130, s[8:9]
	v_exp_f32_e64 v192, -v130
	v_add_f32_e32 v208, v208, v130
	v_pk_add_f32 v[80:81], v[80:81], v[130:131] op_sel_hi:[1,0] neg_lo:[0,1] neg_hi:[0,1]
	v_pk_add_f32 v[82:83], v[82:83], v[130:131] op_sel_hi:[1,0] neg_lo:[0,1] neg_hi:[0,1]
	v_cndmask_b32_e64 v202, v192, 1.0, s[8:9]
	v_pk_add_f32 v[84:85], v[84:85], v[130:131] op_sel_hi:[1,0] neg_lo:[0,1] neg_hi:[0,1]
	v_pk_add_f32 v[86:87], v[86:87], v[130:131] op_sel_hi:[1,0] neg_lo:[0,1] neg_hi:[0,1]
	v_pk_add_f32 v[88:89], v[88:89], v[130:131] op_sel_hi:[1,0] neg_lo:[0,1] neg_hi:[0,1]
	v_pk_add_f32 v[90:91], v[90:91], v[130:131] op_sel_hi:[1,0] neg_lo:[0,1] neg_hi:[0,1]
	v_pk_add_f32 v[92:93], v[92:93], v[130:131] op_sel_hi:[1,0] neg_lo:[0,1] neg_hi:[0,1]
	v_pk_add_f32 v[94:95], v[94:95], v[130:131] op_sel_hi:[1,0] neg_lo:[0,1] neg_hi:[0,1]
	v_pk_add_f32 v[64:65], v[64:65], v[130:131] op_sel_hi:[1,0] neg_lo:[0,1] neg_hi:[0,1]
	v_pk_add_f32 v[66:67], v[66:67], v[130:131] op_sel_hi:[1,0] neg_lo:[0,1] neg_hi:[0,1]
	v_pk_add_f32 v[68:69], v[68:69], v[130:131] op_sel_hi:[1,0] neg_lo:[0,1] neg_hi:[0,1]
	v_pk_add_f32 v[70:71], v[70:71], v[130:131] op_sel_hi:[1,0] neg_lo:[0,1] neg_hi:[0,1]
	v_pk_add_f32 v[72:73], v[72:73], v[130:131] op_sel_hi:[1,0] neg_lo:[0,1] neg_hi:[0,1]
	v_pk_add_f32 v[74:75], v[74:75], v[130:131] op_sel_hi:[1,0] neg_lo:[0,1] neg_hi:[0,1]
	v_pk_add_f32 v[76:77], v[76:77], v[130:131] op_sel_hi:[1,0] neg_lo:[0,1] neg_hi:[0,1]
	v_pk_add_f32 v[78:79], v[78:79], v[130:131] op_sel_hi:[1,0] neg_lo:[0,1] neg_hi:[0,1]
	v_mul_f32_e32 v211, v211, v202
	s_branch .LBB0_731

.LBB0_736:
	s_add_i32 s9, s9, s10
	s_mov_b32 m0, s9
	v_xor_b32_e32 v64, 0x80000000, v208
	v_mov_b32_e32 v65, v64
	buffer_load_dwordx4 v129, s[24:27], s1 offen lds
	v_mov_b64_e32 v[66:67], v[64:65]
	v_mov_b64_e32 v[68:69], v[64:65]
	v_mov_b64_e32 v[70:71], v[64:65]
	v_mov_b64_e32 v[72:73], v[64:65]
	v_mov_b64_e32 v[74:75], v[64:65]
	v_mov_b64_e32 v[76:77], v[64:65]
	v_mov_b64_e32 v[78:79], v[64:65]
	v_max_f32_e32 v130, v113, v113
	s_waitcnt lgkmcnt(2)
	v_mfma_f32_32x32x16_bf16 v[80:95], v[244:247], v[136:139], v[64:79]
	v_max_f32_e32 v184, v112, v112
	v_max_f32_e32 v130, v184, v130
	v_max3_f32 v130, v130, v114, v115
	v_max3_f32 v130, v130, v116, v117
	v_max3_f32 v130, v130, v118, v119
	s_add_i32 m0, s9, 0x2000
	ds_read_b128 v[184:187], v212 offset:96
	buffer_load_dwordx4 v131, s[24:27], s1 offen lds
	s_waitcnt lgkmcnt(2)
	v_mfma_f32_32x32x16_bf16 v[80:95], v[248:251], v[140:143], v[80:95]
	v_max3_f32 v130, v130, v120, v121
	v_max3_f32 v130, v130, v122, v123
	v_max3_f32 v130, v130, v124, v125
	v_max3_f32 v130, v130, v126, v127
	s_add_i32 m0, s9, 0x4000
	ds_read_b128 v[234:237], v212 offset:128
	buffer_load_dwordx4 v199, s[24:27], s1 offen lds
	s_waitcnt lgkmcnt(2)
	v_mfma_f32_32x32x16_bf16 v[80:95], v[230:233], v[144:147], v[80:95]
	v_max3_f32 v130, v130, v96, v97
	v_max3_f32 v130, v130, v98, v99
	v_max3_f32 v130, v130, v100, v101
	v_max3_f32 v130, v130, v102, v103
	s_add_i32 s9, s0, s10
	s_mov_b32 s14, s26
	s_mov_b32 s15, s27
	s_mov_b32 m0, s9
	ds_read_b128 v[188:191], v212 offset:160
	buffer_load_dwordx4 v203, s[12:15], s8 offen lds
	s_waitcnt lgkmcnt(2)
	v_mfma_f32_32x32x16_bf16 v[80:95], v[184:187], v[148:151], v[80:95]
	v_max3_f32 v130, v130, v104, v105
	v_max3_f32 v130, v130, v106, v107
	v_max3_f32 v130, v130, v108, v109
	v_max3_f32 v130, v130, v110, v111
	s_waitcnt lgkmcnt(1)
	v_mfma_f32_32x32x16_bf16 v[80:95], v[234:237], v[152:155], v[80:95]
	v_mov_b32_e32 v192, v130
	s_nop 1
	v_permlane32_swap_b32_e32 v130, v192
	ds_read_b128 v[184:187], v212 offset:192
	v_max_f32_e32 v192, v192, v192
	v_max_f32_e32 v130, v130, v130
	v_max_f32_e32 v130, v130, v192
	v_cmp_lt_f32_e32 vcc, s68, v130
	s_cmp_lg_u64 vcc, 0
	s_cselect_b64 s[0:1], -1, 0
	s_cbranch_vccz .LBB0_739
	v_max_f32_e32 v130, v130, v130
	v_max_f32_e32 v130, 0, v130
	v_exp_f32_e64 v202, -v130
	v_add_f32_e32 v208, v208, v130
	v_pk_add_f32 v[112:113], v[112:113], v[130:131] op_sel_hi:[1,0] neg_lo:[0,1] neg_hi:[0,1]
	v_pk_add_f32 v[114:115], v[114:115], v[130:131] op_sel_hi:[1,0] neg_lo:[0,1] neg_hi:[0,1]
	v_pk_add_f32 v[116:117], v[116:117], v[130:131] op_sel_hi:[1,0] neg_lo:[0,1] neg_hi:[0,1]
	v_pk_add_f32 v[118:119], v[118:119], v[130:131] op_sel_hi:[1,0] neg_lo:[0,1] neg_hi:[0,1]
	v_pk_add_f32 v[120:121], v[120:121], v[130:131] op_sel_hi:[1,0] neg_lo:[0,1] neg_hi:[0,1]
	v_pk_add_f32 v[122:123], v[122:123], v[130:131] op_sel_hi:[1,0] neg_lo:[0,1] neg_hi:[0,1]
	v_pk_add_f32 v[124:125], v[124:125], v[130:131] op_sel_hi:[1,0] neg_lo:[0,1] neg_hi:[0,1]
	v_pk_add_f32 v[126:127], v[126:127], v[130:131] op_sel_hi:[1,0] neg_lo:[0,1] neg_hi:[0,1]
	v_pk_add_f32 v[96:97], v[96:97], v[130:131] op_sel_hi:[1,0] neg_lo:[0,1] neg_hi:[0,1]
	v_pk_add_f32 v[98:99], v[98:99], v[130:131] op_sel_hi:[1,0] neg_lo:[0,1] neg_hi:[0,1]
	v_pk_add_f32 v[100:101], v[100:101], v[130:131] op_sel_hi:[1,0] neg_lo:[0,1] neg_hi:[0,1]
	v_pk_add_f32 v[102:103], v[102:103], v[130:131] op_sel_hi:[1,0] neg_lo:[0,1] neg_hi:[0,1]
	v_pk_add_f32 v[104:105], v[104:105], v[130:131] op_sel_hi:[1,0] neg_lo:[0,1] neg_hi:[0,1]
	v_pk_add_f32 v[106:107], v[106:107], v[130:131] op_sel_hi:[1,0] neg_lo:[0,1] neg_hi:[0,1]
	v_pk_add_f32 v[108:109], v[108:109], v[130:131] op_sel_hi:[1,0] neg_lo:[0,1] neg_hi:[0,1]
	v_pk_add_f32 v[110:111], v[110:111], v[130:131] op_sel_hi:[1,0] neg_lo:[0,1] neg_hi:[0,1]
	v_mul_f32_e32 v211, v211, v202
	s_branch .LBB0_740

; __device__ __forceinline__ void unpack8(const u32x4 w, float (&f)[8]) { f[0] = bflo(w.x); f[1] = bfhi(w.x); f[2] = bflo(w.y); f[3] = bfhi(w.y); f[4] = bflo(w.z); f[5] = bfhi(w.z); f[6] = bflo(w.w); f[7] = bfhi(w.w); }
; __device__ __forceinline__ u32x4 pack8(const float (&f)[8]) { u32x4 w; w.x = cvt_pk_bf16(f[0], f[1]); w.y = cvt_pk_bf16(f[2], f[3]); w.z = cvt_pk_bf16(f[4], f[5]); w.w = cvt_pk_bf16(f[6], f[7]); return w; }
; __device__ __forceinline__ void lds_barrier() { asm volatile("s_waitcnt lgkmcnt(0)\n\ts_barrier" ::: "memory"); }
; __device__ __forceinline__ void mla_unit(const Frame& F, int h, int q0, int key0, int ntiles, int mode, int su) {
;     ...
;     bf16x8 Qf[12];
;     {
;         const bf16_t* qp = Q + (size_t)qr * 1536 + h * QHD;
; #pragma unroll
;         for (int ks = 0; ks < 8; ++ks) { float x[8]; unpack8(*(const u32x4*)(qp + 16 * ks + 8 * hh), x);
; #pragma unroll
;             for (int j = 0; j < 8; ++j) x[j] *= SC;
;             Qf[ks] = __builtin_bit_cast(bf16x8, pack8(x)); }
; #pragma unroll
;         for (int ks = 8; ks < 12; ++ks) {
;             const int d0 = 16 * ks + 8 * hh;
;             const u32x4 own = *(const u32x4*)(qp + d0);
;             if (qr < SEQ) {
;                 const u32x4 par = *(const u32x4*)(qp + d0 + ((ks & 1) ? -16 : 16));
;                 float xo[8], xp[8], o[8]; unpack8(own, xo); unpack8(par, xp);
;                 const float* rp = rope + ((size_t)qr * 32 + ((ks - 8) >> 1) * 16 + 8 * hh) * 2;
; #pragma unroll
;                 for (int j = 0; j < 8; ++j) { const float cs = rp[2 * j], sn = rp[2 * j + 1]; o[j] = SC * ((ks & 1) ? (xp[j] * sn + xo[j] * cs) : (xo[j] * cs - xp[j] * sn)); }
;                 Qf[ks] = __builtin_bit_cast(bf16x8, pack8(o));
;             } else { float x[8]; unpack8(own, x);
; #pragma unroll
;                 for (int j = 0; j < 8; ++j) x[j] *= SC;
;                 Qf[ks] = __builtin_bit_cast(bf16x8, pack8(x)); }
;         }
;     }
;     ...
;     asm volatile("s_waitcnt vmcnt(0)" ::: "memory");
;     lds_barrier();
;     const int krd = ql * MA_KSTR + 16 * hh;
;     const int vrd = (4 * hh + ((F.lane & 15) >> 2)) * MA_VSTR + (((F.lane >> 4) & 1) * 16 + (F.lane & 3) * 4) * 2;
.LBB0_884:
	s_mov_b32 s14, 0x3dd53b94
	v_pk_mul_f32 v[96:97], v[96:97], s[14:15] op_sel_hi:[1,0]
	v_pk_mul_f32 v[98:99], v[98:99], s[14:15] op_sel_hi:[1,0]
	v_cvt_pk_bf16_f32 v145, v96, v97
	v_pk_mul_f32 v[96:97], v[106:107], s[14:15] op_sel_hi:[1,0]
	v_cvt_pk_bf16_f32 v146, v98, v99
	v_cvt_pk_bf16_f32 v150, v96, v97
	v_lshlrev_b32_e32 v96, 16, v92
	v_and_b32_e32 v97, 0xffff0000, v92
	v_lshlrev_b32_e32 v92, 16, v93
	v_and_b32_e32 v93, 0xffff0000, v93
	v_pk_mul_f32 v[92:93], v[92:93], s[14:15] op_sel_hi:[1,0]
	v_pk_mul_f32 v[98:99], v[104:105], s[14:15] op_sel_hi:[1,0]
	v_cvt_pk_bf16_f32 v153, v92, v93
	v_lshlrev_b32_e32 v92, 16, v88
	v_and_b32_e32 v93, 0xffff0000, v88
	v_lshlrev_b32_e32 v88, 16, v89
	v_and_b32_e32 v89, 0xffff0000, v89
	v_pk_mul_f32 v[88:89], v[88:89], s[14:15] op_sel_hi:[1,0]
	v_cvt_pk_bf16_f32 v149, v98, v99
	v_cvt_pk_bf16_f32 v157, v88, v89
	v_lshlrev_b32_e32 v88, 16, v84
	v_and_b32_e32 v89, 0xffff0000, v84
	v_lshlrev_b32_e32 v84, 16, v85
	v_and_b32_e32 v85, 0xffff0000, v85
	v_pk_mul_f32 v[84:85], v[84:85], s[14:15] op_sel_hi:[1,0]
	v_lshlrev_b32_e32 v98, 16, v94
	v_and_b32_e32 v99, 0xffff0000, v94
	v_lshlrev_b32_e32 v94, 16, v95
	v_and_b32_e32 v95, 0xffff0000, v95
	v_cvt_pk_bf16_f32 v161, v84, v85
	v_lshlrev_b32_e32 v84, 16, v80
	v_and_b32_e32 v85, 0xffff0000, v80
	v_lshlrev_b32_e32 v80, 16, v81
	v_and_b32_e32 v81, 0xffff0000, v81
	v_pk_mul_f32 v[94:95], v[94:95], s[14:15] op_sel_hi:[1,0]
	v_pk_mul_f32 v[80:81], v[80:81], s[14:15] op_sel_hi:[1,0]
	v_cvt_pk_bf16_f32 v155, v94, v95
	v_lshlrev_b32_e32 v94, 16, v90
	v_and_b32_e32 v95, 0xffff0000, v90
	v_lshlrev_b32_e32 v90, 16, v91
	v_and_b32_e32 v91, 0xffff0000, v91
	v_cvt_pk_bf16_f32 v165, v80, v81
	v_lshlrev_b32_e32 v80, 16, v76
	v_and_b32_e32 v81, 0xffff0000, v76
	v_lshlrev_b32_e32 v76, 16, v77
	v_and_b32_e32 v77, 0xffff0000, v77
	v_pk_mul_f32 v[90:91], v[90:91], s[14:15] op_sel_hi:[1,0]
	v_pk_mul_f32 v[76:77], v[76:77], s[14:15] op_sel_hi:[1,0]
	v_cvt_pk_bf16_f32 v159, v90, v91
	v_lshlrev_b32_e32 v90, 16, v86
	v_and_b32_e32 v91, 0xffff0000, v86
	v_lshlrev_b32_e32 v86, 16, v87
	v_and_b32_e32 v87, 0xffff0000, v87
	v_cvt_pk_bf16_f32 v169, v76, v77
	v_lshlrev_b32_e32 v76, 16, v72
	v_and_b32_e32 v77, 0xffff0000, v72
	v_lshlrev_b32_e32 v72, 16, v73
	v_and_b32_e32 v73, 0xffff0000, v73
	v_pk_mul_f32 v[86:87], v[86:87], s[14:15] op_sel_hi:[1,0]
	v_pk_mul_f32 v[72:73], v[72:73], s[14:15] op_sel_hi:[1,0]
	v_cvt_pk_bf16_f32 v163, v86, v87
	v_lshlrev_b32_e32 v86, 16, v82
	v_and_b32_e32 v87, 0xffff0000, v82
	v_lshlrev_b32_e32 v82, 16, v83
	v_and_b32_e32 v83, 0xffff0000, v83
	v_cvt_pk_bf16_f32 v173, v72, v73
	v_lshlrev_b32_e32 v72, 16, v68
	v_and_b32_e32 v73, 0xffff0000, v68
	v_lshlrev_b32_e32 v68, 16, v69
	v_and_b32_e32 v69, 0xffff0000, v69
	v_pk_mul_f32 v[82:83], v[82:83], s[14:15] op_sel_hi:[1,0]
	v_pk_mul_f32 v[68:69], v[68:69], s[14:15] op_sel_hi:[1,0]
	v_cvt_pk_bf16_f32 v167, v82, v83
	v_lshlrev_b32_e32 v82, 16, v78
	v_and_b32_e32 v83, 0xffff0000, v78
	v_lshlrev_b32_e32 v78, 16, v79
	v_and_b32_e32 v79, 0xffff0000, v79
	v_cvt_pk_bf16_f32 v177, v68, v69
	v_lshlrev_b32_e32 v68, 16, v64
	v_and_b32_e32 v69, 0xffff0000, v64
	v_lshlrev_b32_e32 v64, 16, v65
	v_and_b32_e32 v65, 0xffff0000, v65
	v_mul_f32_e32 v102, 0x3dd53b94, v121
	s_and_b64 s[8:9], s[0:1], exec
	v_pk_mul_f32 v[78:79], v[78:79], s[14:15] op_sel_hi:[1,0]
	v_pk_mul_f32 v[64:65], v[64:65], s[14:15] op_sel_hi:[1,0]
	v_cvt_pk_bf16_f32 v139, v140, v102
	v_mul_f32_e32 v102, 0x3dd53b94, v113
	v_cvt_pk_bf16_f32 v171, v78, v79
	v_lshlrev_b32_e32 v78, 16, v74
	v_and_b32_e32 v79, 0xffff0000, v74
	v_lshlrev_b32_e32 v74, 16, v75
	v_and_b32_e32 v75, 0xffff0000, v75
	v_cvt_pk_bf16_f32 v181, v64, v65
	v_lshlrev_b32_e32 v64, 4, v131
	s_movk_i32 s8, 0x190
	v_cvt_pk_bf16_f32 v143, v126, v102
	v_mul_f32_e32 v102, 0x3dd53b94, v103
	v_pk_mul_f32 v[74:75], v[74:75], s[14:15] op_sel_hi:[1,0]
	s_waitcnt vmcnt(0)
	v_mad_u32_u24 v212, v129, s8, v64
	v_cvt_pk_bf16_f32 v147, v112, v102
	v_pk_mul_f32 v[100:101], v[100:101], s[14:15] op_sel_hi:[1,0]
	v_mul_f32_e32 v102, 0x3dd53b94, v109
	v_pk_mul_f32 v[98:99], v[98:99], s[14:15] op_sel_hi:[1,0]
	v_cvt_pk_bf16_f32 v175, v74, v75
	v_lshlrev_b32_e32 v74, 16, v70
	v_and_b32_e32 v75, 0xffff0000, v70
	v_lshlrev_b32_e32 v70, 16, v71
	v_and_b32_e32 v71, 0xffff0000, v71
	s_waitcnt lgkmcnt(0)
	s_barrier
; #define LAS __attribute__((address_space(3)))
; #define MFMA32(a, b, c) __builtin_amdgcn_mfma_f32_32x32x16_bf16(a, b, c, 0, 0, 0)
; __device__ __forceinline__ void mla_unit(const Frame& F, int h, int q0, int key0, int ntiles, int mode, int su) {
;     ...
;     const int krd = ql * MA_KSTR + 16 * hh;
;     const int vrd = (4 * hh + ((F.lane & 15) >> 2)) * MA_VSTR + (((F.lane >> 4) & 1) * 16 + (F.lane & 3) * 4) * 2;
;     f32x16 sA[2], sB[2];
;     {   const LAS unsigned char* kb = F.lds + MA_K_OFF + krd;
; #pragma unroll
;         for (int kt = 0; kt < 2; ++kt) { { const float nm = -m;
; #pragma unroll
;             for (int r = 0; r < 16; ++r) sA[kt][r] = nm; }
; #pragma unroll
;             for (int ks = 0; ks < 12; ++ks) { const bf16x8 kf = *(const LAS bf16x8*)(kb + kt * 32 * MA_KSTR + ks * 32); sA[kt] = MFMA32(kf, Qf[ks], sA[kt]); } } }
;     int c0 = 0, c1 = 1, c2 = 2;
	v_add_u32_e32 v213, 0, v212
	v_cvt_pk_bf16_f32 v148, v100, v101
	v_cvt_pk_bf16_f32 v151, v108, v102
	v_pk_mul_f32 v[96:97], v[96:97], s[14:15] op_sel_hi:[1,0]
	v_cvt_pk_bf16_f32 v154, v98, v99
	v_pk_mul_f32 v[70:71], v[70:71], s[14:15] op_sel_hi:[1,0]
	v_lshlrev_b32_e32 v204, 2, v131
	v_lshrrev_b32_e32 v64, 2, v198
	ds_read_b128 v[98:101], v213
	ds_read_b128 v[102:105], v213 offset:32
	v_cvt_pk_bf16_f32 v152, v96, v97
	v_cvt_pk_bf16_f32 v179, v70, v71
	v_lshlrev_b32_e32 v70, 16, v66
	v_and_b32_e32 v71, 0xffff0000, v66
	v_lshlrev_b32_e32 v66, 16, v67
	v_and_b32_e32 v67, 0xffff0000, v67
	v_and_or_b32 v96, v64, 3, v204
	v_and_b32_e32 v64, 16, v198
	v_lshlrev_b32_e32 v65, 2, v198
	v_pk_mul_f32 v[76:77], v[76:77], s[14:15] op_sel_hi:[1,0]
	v_pk_mul_f32 v[78:79], v[78:79], s[14:15] op_sel_hi:[1,0]
	v_pk_mul_f32 v[72:73], v[72:73], s[14:15] op_sel_hi:[1,0]
	v_pk_mul_f32 v[74:75], v[74:75], s[14:15] op_sel_hi:[1,0]
	v_pk_mul_f32 v[68:69], v[68:69], s[14:15] op_sel_hi:[1,0]
	v_pk_mul_f32 v[70:71], v[70:71], s[14:15] op_sel_hi:[1,0]
	v_pk_mul_f32 v[66:67], v[66:67], s[14:15] op_sel_hi:[1,0]
	v_and_or_b32 v97, v65, 12, v64
	s_waitcnt vmcnt(0)
	v_xor_b32_e32 v64, 0x80000000, v199
	v_pk_mul_f32 v[92:93], v[92:93], s[14:15] op_sel_hi:[1,0]
	v_pk_mul_f32 v[94:95], v[94:95], s[14:15] op_sel_hi:[1,0]
	v_pk_mul_f32 v[88:89], v[88:89], s[14:15] op_sel_hi:[1,0]
	v_pk_mul_f32 v[90:91], v[90:91], s[14:15] op_sel_hi:[1,0]
	v_pk_mul_f32 v[84:85], v[84:85], s[14:15] op_sel_hi:[1,0]
	v_pk_mul_f32 v[86:87], v[86:87], s[14:15] op_sel_hi:[1,0]
	v_pk_mul_f32 v[80:81], v[80:81], s[14:15] op_sel_hi:[1,0]
	v_pk_mul_f32 v[82:83], v[82:83], s[14:15] op_sel_hi:[1,0]
	v_cvt_pk_bf16_f32 v172, v76, v77
	v_cvt_pk_bf16_f32 v174, v78, v79
	v_cvt_pk_bf16_f32 v176, v72, v73
	v_cvt_pk_bf16_f32 v178, v74, v75
	v_cvt_pk_bf16_f32 v180, v68, v69
	v_cvt_pk_bf16_f32 v182, v70, v71
	v_cvt_pk_bf16_f32 v183, v66, v67
	v_mov_b32_e32 v65, v64
	v_mov_b64_e32 v[66:67], v[64:65]
	v_mov_b64_e32 v[68:69], v[64:65]
	v_mov_b64_e32 v[70:71], v[64:65]
	v_mov_b64_e32 v[72:73], v[64:65]
	v_mov_b64_e32 v[74:75], v[64:65]
	v_mov_b64_e32 v[76:77], v[64:65]
	v_mov_b64_e32 v[78:79], v[64:65]
	v_cvt_pk_bf16_f32 v156, v92, v93
	v_cvt_pk_bf16_f32 v158, v94, v95
	v_cvt_pk_bf16_f32 v160, v88, v89
	v_cvt_pk_bf16_f32 v162, v90, v91
	v_cvt_pk_bf16_f32 v164, v84, v85
	v_cvt_pk_bf16_f32 v166, v86, v87
	v_cvt_pk_bf16_f32 v168, v80, v81
	v_cvt_pk_bf16_f32 v170, v82, v83
	s_waitcnt lgkmcnt(1)
	v_mfma_f32_32x32x16_bf16 v[80:95], v[98:101], v[152:155], v[64:79]
	ds_read_b128 v[98:101], v213 offset:64
	v_mul_f32_e64 v110, v110, s14
	v_mul_f32_e64 v111, v111, s14
	v_mul_f32_e64 v116, v116, s14
	v_mul_f32_e64 v117, v117, s14
	v_cvt_pk_bf16_f32 v144, v110, v111
	v_pk_mul_f32 v[114:115], v[114:115], s[14:15] op_sel_hi:[1,0]
	v_pk_mul_f32 v[136:137], v[136:137], s[14:15] op_sel_hi:[1,0]
	v_cvt_pk_bf16_f32 v138, v116, v117
	s_waitcnt lgkmcnt(1)
	v_mfma_f32_32x32x16_bf16 v[80:95], v[102:105], v[156:159], v[80:95]
	v_cvt_pk_bf16_f32 v136, v136, v137
	v_cvt_pk_bf16_f32 v137, v114, v115
	v_mul_f32_e64 v114, v124, s14
	v_mul_f32_e64 v115, v125, s14
	v_mul_f32_e64 v116, v122, s14
	v_mul_f32_e64 v117, v123, s14
	v_pk_mul_f32 v[118:119], v[118:119], s[14:15] op_sel_hi:[1,0]
	v_cvt_pk_bf16_f32 v141, v116, v117
	v_cvt_pk_bf16_f32 v140, v118, v119
	s_waitcnt lgkmcnt(0)
	v_mfma_f32_32x32x16_bf16 v[80:95], v[98:101], v[160:163], v[80:95]
	ds_read_b128 v[98:101], v213 offset:96
	v_cvt_pk_bf16_f32 v142, v114, v115
	s_movk_i32 s8, 0x140
	s_movk_i32 s3, 0x42
	v_mul_lo_u32 v96, v96, s8
	s_cselect_b32 s3, s3, 0x84
	v_lshl_or_b32 v216, v97, 1, v96
	s_waitcnt lgkmcnt(0)
	v_mfma_f32_32x32x16_bf16 v[80:95], v[98:101], v[164:167], v[80:95]
	ds_read_b128 v[98:101], v213 offset:128
	s_add_i32 s8, 0, 0x12c00
	v_cndmask_b32_e64 v96, 0, -1, s[0:1]
	s_mov_b32 s16, 2
	s_mov_b32 s17, 1
	s_add_i32 s18, s3, -1
	v_add_u32_e32 v229, s8, v216
	s_waitcnt lgkmcnt(0)
	v_mfma_f32_32x32x16_bf16 v[80:95], v[98:101], v[168:171], v[80:95]
	ds_read_b128 v[98:101], v213 offset:160
	s_mov_b32 s0, 0
	v_readfirstlane_b32 s19, v96
	s_mov_b32 s24, 0
	s_waitcnt lgkmcnt(0)
	v_mfma_f32_32x32x16_bf16 v[80:95], v[98:101], v[172:175], v[80:95]
	ds_read_b128 v[98:101], v213 offset:192
	s_waitcnt lgkmcnt(0)
	v_mfma_f32_32x32x16_bf16 v[80:95], v[98:101], v[176:179], v[80:95]
	ds_read_b128 v[98:101], v213 offset:224
	s_waitcnt lgkmcnt(0)
	v_mfma_f32_32x32x16_bf16 v[80:95], v[98:101], v[180:183], v[80:95]
	ds_read_b128 v[98:101], v213 offset:256
	s_waitcnt lgkmcnt(0)
	v_mfma_f32_32x32x16_bf16 v[80:95], v[98:101], v[148:151], v[80:95]
	ds_read_b128 v[98:101], v213 offset:288
	s_waitcnt lgkmcnt(0)
	v_mfma_f32_32x32x16_bf16 v[80:95], v[98:101], v[144:147], v[80:95]
	ds_read_b128 v[98:101], v213 offset:320
	s_waitcnt lgkmcnt(0)
	v_mfma_f32_32x32x16_bf16 v[80:95], v[98:101], v[140:143], v[80:95]
	ds_read_b128 v[98:101], v213 offset:352
	s_waitcnt lgkmcnt(0)
	v_mfma_f32_32x32x16_bf16 v[80:95], v[98:101], v[136:139], v[80:95]
	ds_read_b128 v[98:101], v213 offset:12800
	s_waitcnt lgkmcnt(0)
	v_mfma_f32_32x32x16_bf16 v[64:79], v[98:101], v[152:155], v[64:79]
	ds_read_b128 v[98:101], v213 offset:12832
	s_waitcnt lgkmcnt(0)
	v_mfma_f32_32x32x16_bf16 v[64:79], v[98:101], v[156:159], v[64:79]
	ds_read_b128 v[98:101], v213 offset:12864
	s_waitcnt lgkmcnt(0)
	v_mfma_f32_32x32x16_bf16 v[64:79], v[98:101], v[160:163], v[64:79]
	ds_read_b128 v[98:101], v213 offset:12896
	s_waitcnt lgkmcnt(0)
	v_mfma_f32_32x32x16_bf16 v[64:79], v[98:101], v[164:167], v[64:79]
	ds_read_b128 v[98:101], v213 offset:12928
	s_waitcnt lgkmcnt(0)
	v_mfma_f32_32x32x16_bf16 v[64:79], v[98:101], v[168:171], v[64:79]
	ds_read_b128 v[98:101], v213 offset:12960
	s_waitcnt lgkmcnt(0)
	v_mfma_f32_32x32x16_bf16 v[64:79], v[98:101], v[172:175], v[64:79]
	ds_read_b128 v[98:101], v213 offset:12992
	s_waitcnt lgkmcnt(0)
	v_mfma_f32_32x32x16_bf16 v[64:79], v[98:101], v[176:179], v[64:79]
	ds_read_b128 v[98:101], v213 offset:13024
	s_waitcnt lgkmcnt(0)
	v_mfma_f32_32x32x16_bf16 v[64:79], v[98:101], v[180:183], v[64:79]
	ds_read_b128 v[98:101], v213 offset:13056
	s_waitcnt lgkmcnt(0)
	v_mfma_f32_32x32x16_bf16 v[64:79], v[98:101], v[148:151], v[64:79]
	ds_read_b128 v[98:101], v213 offset:13088
	s_waitcnt lgkmcnt(0)
	v_mfma_f32_32x32x16_bf16 v[64:79], v[98:101], v[144:147], v[64:79]
	ds_read_b128 v[98:101], v213 offset:13120
	s_waitcnt lgkmcnt(0)
	v_mfma_f32_32x32x16_bf16 v[64:79], v[98:101], v[140:143], v[64:79]
	ds_read_b128 v[98:101], v213 offset:13152
	s_waitcnt lgkmcnt(0)
	v_mfma_f32_32x32x16_bf16 v[64:79], v[98:101], v[136:139], v[64:79]
	v_readlane_b32 s36, v253, 22
	v_readlane_b32 s37, v253, 23
	v_readlane_b32 s38, v253, 24
	v_readlane_b32 s39, v253, 25
	s_nop 4
	s_mul_i32 s40, s17, 0x6400
	v_add_u32_e32 v230, s40, v213
	ds_read_b128 v[244:247], v230
	ds_read_b128 v[248:251], v230 offset:32
	ds_read_b128 v[232:235], v230 offset:64

.LBB0_889:
	s_mul_i32 s1, s21, 0x6400
	s_cmp_eq_u32 s19, s24
	s_cselect_b64 s[8:9], -1, 0
	s_add_i32 s1, s23, s10
	s_mov_b32 m0, s1
	v_xor_b32_e32 v96, 0x80000000, v199
	v_mov_b32_e32 v97, v96
	buffer_load_dwordx4 v201, s[36:39], s0 offen lds
	v_mov_b64_e32 v[98:99], v[96:97]
	v_mov_b64_e32 v[100:101], v[96:97]
	v_mov_b64_e32 v[102:103], v[96:97]
	v_mov_b64_e32 v[104:105], v[96:97]
	v_mov_b64_e32 v[106:107], v[96:97]
	v_mov_b64_e32 v[108:109], v[96:97]
	v_mov_b64_e32 v[110:111], v[96:97]
	s_waitcnt lgkmcnt(2)
	s_nop 0
	v_mfma_f32_32x32x16_bf16 v[112:127], v[244:247], v[152:155], v[96:111]
	v_max_f32_e32 v184, v81, v81
	v_max_f32_e32 v185, v80, v80
	v_max_f32_e32 v184, v185, v184
	v_max3_f32 v184, v184, v82, v83
	v_max3_f32 v184, v184, v84, v85
	v_max3_f32 v192, v184, v86, v87
	s_add_i32 m0, s1, 0x2000
	ds_read_b128 v[184:187], v230 offset:96
	buffer_load_dwordx4 v203, s[36:39], s0 offen lds
	s_waitcnt lgkmcnt(2)
	v_mfma_f32_32x32x16_bf16 v[112:127], v[248:251], v[156:159], v[112:127]
	v_max3_f32 v188, v192, v88, v89
	v_max3_f32 v188, v188, v90, v91
	v_max3_f32 v188, v188, v92, v93
	v_max3_f32 v188, v188, v94, v95
	s_add_i32 m0, s1, 0x4000
	ds_read_b128 v[236:239], v230 offset:128
	buffer_load_dwordx4 v205, s[36:39], s0 offen lds
	s_waitcnt lgkmcnt(2)
	v_mfma_f32_32x32x16_bf16 v[112:127], v[232:235], v[160:163], v[112:127]
	v_max3_f32 v188, v188, v64, v65
	v_max3_f32 v188, v188, v66, v67
	v_max3_f32 v188, v188, v68, v69
	v_max3_f32 v192, v188, v70, v71
	s_add_i32 s26, s26, s10
	s_mov_b32 s14, s38
	s_mov_b32 s15, s39
	s_mov_b32 m0, s26
	ds_read_b128 v[188:191], v230 offset:160
	buffer_load_dwordx4 v209, s[12:15], s25 offen lds
	s_waitcnt lgkmcnt(2)
	v_mfma_f32_32x32x16_bf16 v[112:127], v[184:187], v[164:167], v[112:127]
	v_max3_f32 v184, v192, v72, v73
	v_max3_f32 v184, v184, v74, v75
	v_max3_f32 v184, v184, v76, v77
	v_max3_f32 v192, v184, v78, v79
	v_mov_b32_e32 v193, v192
	s_waitcnt lgkmcnt(1)
	v_mfma_f32_32x32x16_bf16 v[112:127], v[236:239], v[168:171], v[112:127]
	v_permlane32_swap_b32_e32 v192, v193
	v_max_f32_e32 v193, v193, v193
	v_max_f32_e32 v192, v192, v192
	v_max_f32_e32 v206, v192, v193
	ds_read_b128 v[184:187], v230 offset:192
	v_cmp_lt_f32_e32 vcc, s68, v206
	s_cmp_lg_u64 vcc, 0
	s_cselect_b64 s[0:1], -1, 0
	s_or_b64 s[0:1], s[8:9], s[0:1]
	s_and_b64 vcc, exec, s[0:1]
	s_cbranch_vccz .LBB0_891
	v_max_f32_e32 v192, v206, v206
	v_max_f32_e32 v192, 0, v192
	v_cndmask_b32_e64 v206, v192, v206, s[8:9]
	v_exp_f32_e64 v192, -v206
	v_add_f32_e32 v199, v199, v206
	v_pk_add_f32 v[80:81], v[80:81], v[206:207] op_sel_hi:[1,0] neg_lo:[0,1] neg_hi:[0,1]
	v_pk_add_f32 v[82:83], v[82:83], v[206:207] op_sel_hi:[1,0] neg_lo:[0,1] neg_hi:[0,1]
	v_cndmask_b32_e64 v208, v192, 1.0, s[8:9]
	v_pk_add_f32 v[84:85], v[84:85], v[206:207] op_sel_hi:[1,0] neg_lo:[0,1] neg_hi:[0,1]
	v_pk_add_f32 v[86:87], v[86:87], v[206:207] op_sel_hi:[1,0] neg_lo:[0,1] neg_hi:[0,1]
	v_pk_add_f32 v[88:89], v[88:89], v[206:207] op_sel_hi:[1,0] neg_lo:[0,1] neg_hi:[0,1]
	v_pk_add_f32 v[90:91], v[90:91], v[206:207] op_sel_hi:[1,0] neg_lo:[0,1] neg_hi:[0,1]
	v_pk_add_f32 v[92:93], v[92:93], v[206:207] op_sel_hi:[1,0] neg_lo:[0,1] neg_hi:[0,1]
	v_pk_add_f32 v[94:95], v[94:95], v[206:207] op_sel_hi:[1,0] neg_lo:[0,1] neg_hi:[0,1]
	v_pk_add_f32 v[64:65], v[64:65], v[206:207] op_sel_hi:[1,0] neg_lo:[0,1] neg_hi:[0,1]
	v_pk_add_f32 v[66:67], v[66:67], v[206:207] op_sel_hi:[1,0] neg_lo:[0,1] neg_hi:[0,1]
	v_pk_add_f32 v[68:69], v[68:69], v[206:207] op_sel_hi:[1,0] neg_lo:[0,1] neg_hi:[0,1]
	v_pk_add_f32 v[70:71], v[70:71], v[206:207] op_sel_hi:[1,0] neg_lo:[0,1] neg_hi:[0,1]
	v_pk_add_f32 v[72:73], v[72:73], v[206:207] op_sel_hi:[1,0] neg_lo:[0,1] neg_hi:[0,1]
	v_pk_add_f32 v[74:75], v[74:75], v[206:207] op_sel_hi:[1,0] neg_lo:[0,1] neg_hi:[0,1]
	v_pk_add_f32 v[76:77], v[76:77], v[206:207] op_sel_hi:[1,0] neg_lo:[0,1] neg_hi:[0,1]
	v_pk_add_f32 v[78:79], v[78:79], v[206:207] op_sel_hi:[1,0] neg_lo:[0,1] neg_hi:[0,1]
	v_mul_f32_e32 v214, v214, v208
	s_branch .LBB0_892

.LBB0_897:
	s_add_i32 s9, s9, s10
	s_mov_b32 m0, s9
	v_xor_b32_e32 v64, 0x80000000, v199
	v_mov_b32_e32 v65, v64
	buffer_load_dwordx4 v201, s[36:39], s1 offen lds
	v_mov_b64_e32 v[66:67], v[64:65]
	v_mov_b64_e32 v[68:69], v[64:65]
	v_mov_b64_e32 v[70:71], v[64:65]
	v_mov_b64_e32 v[72:73], v[64:65]
	v_mov_b64_e32 v[74:75], v[64:65]
	v_mov_b64_e32 v[76:77], v[64:65]
	v_mov_b64_e32 v[78:79], v[64:65]
	s_waitcnt lgkmcnt(2)
	s_nop 0
	v_mfma_f32_32x32x16_bf16 v[80:95], v[244:247], v[152:155], v[64:79]
	v_max_f32_e32 v184, v113, v113
	v_max_f32_e32 v185, v112, v112
	v_max_f32_e32 v184, v185, v184
	v_max3_f32 v184, v184, v114, v115
	v_max3_f32 v184, v184, v116, v117
	v_max3_f32 v192, v184, v118, v119
	s_add_i32 m0, s9, 0x2000
	ds_read_b128 v[184:187], v230 offset:96
	buffer_load_dwordx4 v203, s[36:39], s1 offen lds
	s_waitcnt lgkmcnt(2)
	v_mfma_f32_32x32x16_bf16 v[80:95], v[248:251], v[156:159], v[80:95]
	v_max3_f32 v188, v192, v120, v121
	v_max3_f32 v188, v188, v122, v123
	v_max3_f32 v188, v188, v124, v125
	v_max3_f32 v188, v188, v126, v127
	s_add_i32 m0, s9, 0x4000
	ds_read_b128 v[236:239], v230 offset:128
	buffer_load_dwordx4 v205, s[36:39], s1 offen lds
	s_waitcnt lgkmcnt(2)
	v_mfma_f32_32x32x16_bf16 v[80:95], v[232:235], v[160:163], v[80:95]
	v_max3_f32 v188, v188, v96, v97
	v_max3_f32 v188, v188, v98, v99
	v_max3_f32 v188, v188, v100, v101
	v_max3_f32 v192, v188, v102, v103
	s_add_i32 s9, s0, s10
	s_mov_b32 s14, s38
	s_mov_b32 s15, s39
	s_mov_b32 m0, s9
	ds_read_b128 v[188:191], v230 offset:160
	buffer_load_dwordx4 v209, s[12:15], s8 offen lds
	s_waitcnt lgkmcnt(2)
	v_mfma_f32_32x32x16_bf16 v[80:95], v[184:187], v[164:167], v[80:95]
	v_max3_f32 v184, v192, v104, v105
	v_max3_f32 v184, v184, v106, v107
	v_max3_f32 v184, v184, v108, v109
	v_max3_f32 v192, v184, v110, v111
	s_waitcnt lgkmcnt(1)
	v_mfma_f32_32x32x16_bf16 v[80:95], v[236:239], v[168:171], v[80:95]
	v_mov_b32_e32 v193, v192
	s_nop 1
	v_permlane32_swap_b32_e32 v192, v193
	ds_read_b128 v[184:187], v230 offset:192
	v_max_f32_e32 v193, v193, v193
	v_max_f32_e32 v192, v192, v192
	v_max_f32_e32 v206, v192, v193
	v_cmp_lt_f32_e32 vcc, s68, v206
	s_cmp_lg_u64 vcc, 0
	s_cselect_b64 s[0:1], -1, 0
	s_cbranch_vccz .LBB0_900
	v_max_f32_e32 v192, v206, v206
	v_max_f32_e32 v206, 0, v192
	v_exp_f32_e64 v208, -v206
	v_add_f32_e32 v199, v199, v206
	v_pk_add_f32 v[112:113], v[112:113], v[206:207] op_sel_hi:[1,0] neg_lo:[0,1] neg_hi:[0,1]
	v_pk_add_f32 v[114:115], v[114:115], v[206:207] op_sel_hi:[1,0] neg_lo:[0,1] neg_hi:[0,1]
	v_pk_add_f32 v[116:117], v[116:117], v[206:207] op_sel_hi:[1,0] neg_lo:[0,1] neg_hi:[0,1]
	v_pk_add_f32 v[118:119], v[118:119], v[206:207] op_sel_hi:[1,0] neg_lo:[0,1] neg_hi:[0,1]
	v_pk_add_f32 v[120:121], v[120:121], v[206:207] op_sel_hi:[1,0] neg_lo:[0,1] neg_hi:[0,1]
	v_pk_add_f32 v[122:123], v[122:123], v[206:207] op_sel_hi:[1,0] neg_lo:[0,1] neg_hi:[0,1]
	v_pk_add_f32 v[124:125], v[124:125], v[206:207] op_sel_hi:[1,0] neg_lo:[0,1] neg_hi:[0,1]
	v_pk_add_f32 v[126:127], v[126:127], v[206:207] op_sel_hi:[1,0] neg_lo:[0,1] neg_hi:[0,1]
	v_pk_add_f32 v[96:97], v[96:97], v[206:207] op_sel_hi:[1,0] neg_lo:[0,1] neg_hi:[0,1]
	v_pk_add_f32 v[98:99], v[98:99], v[206:207] op_sel_hi:[1,0] neg_lo:[0,1] neg_hi:[0,1]
	v_pk_add_f32 v[100:101], v[100:101], v[206:207] op_sel_hi:[1,0] neg_lo:[0,1] neg_hi:[0,1]
	v_pk_add_f32 v[102:103], v[102:103], v[206:207] op_sel_hi:[1,0] neg_lo:[0,1] neg_hi:[0,1]
	v_pk_add_f32 v[104:105], v[104:105], v[206:207] op_sel_hi:[1,0] neg_lo:[0,1] neg_hi:[0,1]
	v_pk_add_f32 v[106:107], v[106:107], v[206:207] op_sel_hi:[1,0] neg_lo:[0,1] neg_hi:[0,1]
	v_pk_add_f32 v[108:109], v[108:109], v[206:207] op_sel_hi:[1,0] neg_lo:[0,1] neg_hi:[0,1]
	v_pk_add_f32 v[110:111], v[110:111], v[206:207] op_sel_hi:[1,0] neg_lo:[0,1] neg_hi:[0,1]
	v_mul_f32_e32 v214, v214, v208
	s_branch .LBB0_901

; #define LAS __attribute__((address_space(3)))
; __device__ __forceinline__ unsigned cvt_pk_bf16(float lo, float hi) { return __builtin_bit_cast(unsigned, __builtin_convertvector((f32x2){lo, hi}, bf16x2n)); }
; __device__ __forceinline__ void lds_barrier() { asm volatile("s_waitcnt lgkmcnt(0)\n\ts_barrier" ::: "memory"); }
; __device__ __forceinline__ void na_unit(const Frame& F, int l, int gi, int hp) {
;     ...
;     unsigned ko[3], vo[3];
; #pragma unroll
;     for (int i = 0; i < 3; ++i) { const int sl = ((i < 2) ? (F.wave + 8 * i) : (16 + (F.wave & 1))) * 64 + F.lane, key = sl / 18, part = sl - key * 18;
;         const unsigned e = (unsigned)(key * IN_COLS + NA_OFF + hp * 128 + ((part < 16) ? part : 0) * 8);
;         ko[i] = (e + 1024u) * 2u; vo[i] = (e + 2048u) * 2u; }
;     const __amdgpu_buffer_rsrc_t rU = __builtin_amdgcn_make_buffer_rsrc((void*)U, 0, 0x7ffffff0, 0x00020000);
;     ...
;     __syncthreads();
;     if (lat) { LAS float* rp = (LAS float*)(F.lds + NA_RPB_OFF); const float* src = F.in[I_RPB] + ((size_t)l * 16 + hp * 2) * 465;
;         for (int i = F.tid; i < 930; i += NTHREADS) rp[i] = src[i] * LOG2E; }
;     NA_DMA(0, 0); NA_DMA(1, 1);
;     asm volatile("s_waitcnt vmcnt(0)" ::: "memory");
;     lds_barrier();
;     const int c0 = (g4 == 0) ? 0 : (g4 == 1 ? 8 : (g4 == 2 ? 24 : 32));
;     const int qc = 16 * g4 + qi, cs_ = min(max(qc - 8, 0), 48);
;     const int krd = qi * NA_KSTR + hh * 128 + 16 * g;
;     const int vrd = (4 * g + (qi >> 2)) * NA_VSTR + hh * 128 + (qi & 3) * 8;
;     const LAS float* rpb = (const LAS float*)(F.lds + NA_RPB_OFF) + hh * 465;
;     int sc = 0, sn2 = 2;
;     ...
;     const float lt = rows_sum(lsum);
;     const float inv = 1.0f / lt;
;     bf16_t* op = YC + (size_t)qr * 3072 + 2048 + h * 64 + 4 * g;
; #pragma unroll
;     for (int dt = 0; dt < 4; ++dt) { const f32x4 o = O[dt] * inv; u32x2 w; w.x = cvt_pk_bf16(o[0], o[1]); w.y = cvt_pk_bf16(o[2], o[3]); *(u32x2*)(op + dt * 16) = w; }
.LBB0_954:
	v_readlane_b32 s0, v254, 21
	v_readlane_b32 s1, v254, 22
	s_andn2_b64 vcc, exec, s[0:1]
	s_cbranch_vccnz .LBB0_1021
	s_mov_b32 s8, 0x38e38e39
	v_mul_hi_i32 v0, v130, s8
	v_lshrrev_b32_e32 v1, 31, v0
	v_ashrrev_i32_e32 v0, 2, v0
	v_add_u32_e32 v2, v0, v1
	s_movk_i32 s9, 0xffee
	v_mad_u64_u32 v[0:1], s[6:7], v2, s9, v[130:131]
	v_lshlrev_b32_e32 v1, 3, v0
	v_cmp_gt_i32_e32 vcc, 16, v0
	s_movk_i32 s10, 0x3500
	s_lshl_b32 s72, s92, 6
	v_cndmask_b32_e32 v0, 0, v1, vcc
	v_mad_u64_u32 v[42:43], s[6:7], v2, s10, v[0:1]
	v_add_u32_e32 v0, 0x200, v130
	v_mul_hi_i32 v1, v0, s8
	s_lshl_b32 s48, s92, 4
	s_lshl_b64 s[0:1], s[72:73], 2
	v_lshrrev_b32_e32 v2, 31, v1
	v_ashrrev_i32_e32 v1, 2, v1
	s_add_u32 s0, s80, s0
	v_add_u32_e32 v1, v1, v2
	s_addc_u32 s1, s81, s1
	v_mad_u64_u32 v[2:3], s[6:7], v1, s9, v[0:1]
	s_add_u32 s0, s0, 0x8000
	v_lshlrev_b32_e32 v3, 3, v2
	v_cmp_gt_i32_e32 vcc, 16, v2
	s_addc_u32 s1, s1, 0
	s_add_u32 s2, s80, 0x6584000
	v_cndmask_b32_e32 v2, 0, v3, vcc
	v_mad_u64_u32 v[44:45], s[6:7], v1, s10, v[2:3]
	s_addc_u32 s3, s81, 0
	s_and_b32 s6, s20, 64
	v_add_u32_e32 v1, s6, v198
	v_add_u32_e32 v2, 0x400, v1
	v_mul_hi_i32 v1, v2, s8
	v_lshrrev_b32_e32 v3, 31, v1
	v_ashrrev_i32_e32 v1, 2, v1
	v_add_u32_e32 v1, v1, v3
	v_mad_u64_u32 v[2:3], s[6:7], v1, s9, v[2:3]
	v_lshlrev_b32_e32 v3, 3, v2
	v_cmp_gt_i32_e32 vcc, 16, v2
	s_and_b32 s49, s82, 3
	s_ashr_i32 s50, s82, 2
	v_cndmask_b32_e32 v2, 0, v3, vcc
	v_mad_u64_u32 v[46:47], s[6:7], v1, s10, v[2:3]
	v_readlane_b32 s8, v253, 22
	v_readlane_b32 s9, v253, 23
	v_readlane_b32 s10, v253, 24
	v_readlane_b32 s11, v253, 25
	s_and_b32 s9, s3, 0xffff
	s_mov_b32 s8, s2
	v_writelane_b32 v253, s8, 22
	s_lshl_b32 s12, s49, 4
	v_writelane_b32 v255, s60, 4
	v_writelane_b32 v253, s9, 23
	v_writelane_b32 v253, s10, 24
	v_writelane_b32 v253, s11, 25
	s_lshl_b32 s8, s82, 10
	s_add_i32 s51, s8, 0
	s_add_i32 s52, s51, 0xd800
	s_add_i32 s53, s51, 0x2000
	s_add_i32 s54, s51, 0xf800
	s_cmp_lt_i32 s82, 2
	s_cselect_b64 s[30:31], -1, 0
	s_cmp_gt_i32 s82, 1
	v_writelane_b32 v255, s61, 5
	v_and_b32_e32 v4, 15, v198
	s_cselect_b64 s[34:35], -1, 0
	s_add_i32 s55, s51, 0x11800
	s_add_i32 s60, s51, 0x4000
	s_add_i32 s61, s51, 0x4800
	s_add_i32 s62, s51, 0x12000
	s_add_i32 s63, s51, 0x6800
	s_add_i32 s64, s51, 0x14000
	s_add_i32 s65, s51, 0x16000
	s_add_i32 s66, s51, 0x8800
	s_cmp_eq_u32 s49, 2
	v_or_b32_e32 v43, s12, v4
	s_cselect_b32 s67, 24, 32
	v_sub_u32_e64 v1, v43, 8 clamp
	s_lshl_b32 s8, s50, 7
	v_min_u32_e32 v45, 48, v1
	v_mul_u32_u24_e32 v1, 0x120, v4
	v_and_b32_e32 v2, -16, v198
	s_add_i32 s8, s8, 0
	v_add3_u32 v47, s8, v1, v2
	v_max_i32_e32 v1, 0x1a2, v130
	v_ashrrev_i32_e32 v5, 4, v198
	v_sub_u32_e32 v1, v1, v130
	v_lshlrev_b32_e32 v48, 2, v5
	v_bfe_u32 v3, v198, 2, 2
	v_add_u32_e32 v1, 0x1ff, v1
	v_lshlrev_b32_e32 v40, 3, v5
	v_or_b32_e32 v3, v48, v3
	s_movk_i32 s9, 0x120
	v_lshlrev_b32_e32 v5, 3, v198
	v_lshrrev_b32_e32 v2, 9, v1
	s_lshl_b32 s14, s82, 8
	v_mul_lo_u32 v3, v3, s9
	v_and_b32_e32 v5, 24, v5
	s_mul_i32 s13, s50, 0x744
	v_add_u32_e32 v2, 1, v2
	v_mov_b32_e32 v131, v0
	s_add_i32 s14, s14, 0
	v_sub_u32_e32 v0, v48, v4
	s_movk_i32 s6, 0x3a2
	v_add3_u32 v50, s8, v3, v5
	s_movk_i32 s8, 0x1ff
	v_and_b32_e32 v51, 0xfffffe, v2
	s_add_i32 s14, s14, 0x1b800
	s_add_i32 s68, s13, 0
	v_subrev_u32_e32 v54, s12, v0
	s_mov_b32 s77, s73
	v_cmp_eq_u32_e64 s[4:5], 0, v130
	s_mov_b64 s[28:29], s[80:81]
	v_ashrrev_i32_e32 v41, 31, v40
	v_cmp_gt_i32_e64 s[6:7], s6, v130
	v_ashrrev_i32_e32 v49, 31, v48
	v_cmp_lt_u32_e64 s[8:9], s8, v1
	v_lshl_add_u32 v52, v51, 9, v130
	v_cmp_ne_u32_e64 s[10:11], v2, v51
	v_lshl_add_u32 v53, v198, 2, s14
	s_add_i32 s68, s68, 0x1b364
	v_add_u32_e32 v55, 19, v54
	v_add_u32_e32 v56, 18, v54
	v_add_u32_e32 v57, 17, v54
	v_add_u32_e32 v58, 16, v54
	v_add_u32_e32 v59, 3, v54
	v_add_u32_e32 v60, 2, v54
	v_add_u32_e32 v61, 1, v54
	s_mov_b32 s56, s82
	s_mov_b32 s72, s84
	s_movk_i32 s73, 0x1800
	v_readlane_b32 s16, v254, 34
	s_and_saveexec_b64 s[12:13], s[4:5]
	s_cbranch_execz .Lmy_nala_skip
	v_mov_b64_e32 v[0:1], s[0:1]
	global_atomic_add v250, v[0:1], v217, off sc0
.Lmy_nala_skip:
	s_or_b64 exec, exec, s[12:13]
	s_branch .LBB0_958
.LBB0_956:
	s_mov_b32 s94, 0x60000
	v_readlane_b32 s92, v255, 0
	v_readlane_b32 s95, v255, 2
	v_readlane_b32 s93, v255, 1
	v_mov_b32_e32 v1, v0
	s_nop 1
	v_permlane16_swap_b32_e32 v0, v1
	v_add_f32_e32 v0, v0, v1
	v_mov_b32_e32 v1, v0
	s_nop 1
	v_permlane32_swap_b32_e32 v0, v1
	v_add_f32_e32 v0, v0, v1
	v_div_scale_f32 v1, s[12:13], v0, v0, 1.0
	v_rcp_f32_e32 v2, v1
	s_mov_b32 s58, 0x90000
	v_readlane_b32 s16, v254, 34
	v_fma_f32 v3, -v1, v2, 1.0
	v_fmac_f32_e32 v2, v3, v2
	v_div_scale_f32 v3, vcc, 1.0, v0, 1.0
	v_mul_f32_e32 v4, v3, v2
	v_fma_f32 v5, -v1, v4, v3
	v_fmac_f32_e32 v4, v5, v2
	v_fma_f32 v1, -v1, v4, v3
	v_div_fmas_f32 v1, v1, v2, v4
	v_mov_b64_e32 v[2:3], s[28:29]
	v_mad_i64_i32 v[2:3], s[12:13], v62, s73, v[2:3]
	v_lshl_add_u64 v[2:3], s[36:37], 1, v[2:3]
	v_lshl_add_u64 v[2:3], v[48:49], 1, v[2:3]
	s_mov_b64 s[12:13], 0x52525000
	v_div_fixup_f32 v0, v1, v0, 1.0
	v_lshl_add_u64 v[4:5], v[2:3], 0, s[12:13]
	s_mov_b32 s12, 0x52525000
	v_pk_mul_f32 v[6:7], v[26:27], v[0:1] op_sel_hi:[1,0]
	v_pk_mul_f32 v[8:9], v[24:25], v[0:1] op_sel_hi:[1,0]
	v_add_co_u32_e32 v2, vcc, s12, v2
	v_cvt_pk_bf16_f32 v8, v8, v9
	v_cvt_pk_bf16_f32 v9, v6, v7
	v_addc_co_u32_e32 v3, vcc, 0, v3, vcc
	flat_store_dwordx2 v[2:3], v[8:9]
	v_pk_mul_f32 v[2:3], v[22:23], v[0:1] op_sel_hi:[1,0]
	v_pk_mul_f32 v[6:7], v[20:21], v[0:1] op_sel_hi:[1,0]
	s_mov_b64 s[12:13], 0
	v_cvt_pk_bf16_f32 v6, v6, v7
	v_cvt_pk_bf16_f32 v7, v2, v3
	flat_store_dwordx2 v[4:5], v[6:7] offset:32
	v_pk_mul_f32 v[2:3], v[18:19], v[0:1] op_sel_hi:[1,0]
	v_pk_mul_f32 v[6:7], v[16:17], v[0:1] op_sel_hi:[1,0]
	s_nop 0
	v_cvt_pk_bf16_f32 v6, v6, v7
	v_cvt_pk_bf16_f32 v7, v2, v3
	v_pk_mul_f32 v[2:3], v[30:31], v[0:1] op_sel_hi:[1,0]
	v_pk_mul_f32 v[0:1], v[28:29], v[0:1] op_sel_hi:[1,0]
	flat_store_dwordx2 v[4:5], v[6:7] offset:64
	v_cvt_pk_bf16_f32 v0, v0, v1
	v_cvt_pk_bf16_f32 v1, v2, v3
	flat_store_dwordx2 v[4:5], v[0:1] offset:96

; __device__ __forceinline__ void attn_phase(const Frame& F, int l, int flags) {
;     ...
;         for (;;) {
;             __syncthreads();
;             if (F.tid == 0) *slot = __hip_atomic_fetch_add(q, 1u, __ATOMIC_RELAXED, __HIP_MEMORY_SCOPE_AGENT);
;             __syncthreads();
;             const int u = (int)*slot;
.LBB0_958:
	s_waitcnt vmcnt(0) lgkmcnt(0)
	s_barrier
	s_and_saveexec_b64 s[12:13], s[4:5]
	s_cbranch_execz .LBB0_960
	v_mov_b32_e32 v1, s16
	ds_write_b32 v1, v250
	v_mov_b64_e32 v[0:1], s[0:1]
	global_atomic_add v250, v[0:1], v217, off sc0
	s_nop 0

; __device__ __forceinline__ void na_unit(const Frame& F, int l, int gi, int hp) {
;     ...
;             if (win) {
;                 const int dr = (r0 + p) - gi + 7;
; #pragma unroll
;                 for (int ks = 0; ks < 2; ++ks)
; #pragma unroll
;                     for (int j = 0; j < 4; ++j) {
;                         const int cc = c0 + 16 * ks + 4 * g + j, rel = cc - cs_;
;                         const bool valid = (rel >= 0) && (rel < 16);
;                         const int bi = min(max(cc - qc + 15, 0), 30);
;                         const float bias = rpb[dr * 31 + bi];
;                         s[ks][j] = valid ? (s[ks][j] * SC + bias) : NEG_BIG;
;                     }
.LBB0_980:
	v_add_u32_e32 v0, s45, v48
	v_or_b32_e32 v2, 1, v0
	v_sub_u32_e32 v2, v2, v45
	v_sub_u32_e32 v1, v0, v45
	v_cmp_gt_u32_e64 s[14:15], 16, v2
	v_or_b32_e32 v2, 2, v0
	v_or_b32_e32 v0, 3, v0
	v_sub_u32_e32 v0, v0, v45
	v_cmp_gt_u32_e64 s[18:19], 16, v0
	v_add_u32_e32 v0, 16, v1
	v_cmp_gt_u32_e64 s[20:21], 16, v0
	v_add_u32_e32 v0, 17, v1
	v_cmp_gt_u32_e64 s[22:23], 16, v0
	v_add_u32_e32 v0, 18, v1
	v_cmp_gt_u32_e64 s[24:25], 16, v0
	v_add_u32_e32 v0, 19, v1
	v_cmp_gt_u32_e64 s[26:27], 16, v0
	v_add_u32_e32 v0, s45, v55
	v_max_i32_e32 v0, -15, v0
	v_add_u32_e32 v0, 15, v0
	s_mulk_i32 s44, 0x7c
	v_min_u32_e32 v0, 30, v0
	v_lshl_add_u32 v0, v0, 2, s44
	s_mulk_i32 s43, 0x7c
	v_subrev_u32_e32 v0, s43, v0
	v_add_u32_e32 v69, s68, v0
	v_add_u32_e32 v0, s45, v56
	v_max_i32_e32 v0, -15, v0
	v_add_u32_e32 v0, 15, v0
	v_min_u32_e32 v0, 30, v0
	v_lshl_add_u32 v0, v0, 2, s44
	v_subrev_u32_e32 v0, s43, v0
	v_add_u32_e32 v70, s68, v0
	v_add_u32_e32 v0, s45, v57
	v_max_i32_e32 v0, -15, v0
	v_add_u32_e32 v0, 15, v0
	v_min_u32_e32 v0, 30, v0
	v_lshl_add_u32 v0, v0, 2, s44
	v_subrev_u32_e32 v0, s43, v0
	v_add_u32_e32 v71, s68, v0
	v_add_u32_e32 v0, s45, v58
	v_max_i32_e32 v0, -15, v0
	v_add_u32_e32 v0, 15, v0
	v_min_u32_e32 v0, 30, v0
	v_lshl_add_u32 v0, v0, 2, s44
	v_subrev_u32_e32 v0, s43, v0
	v_add_u32_e32 v72, s68, v0
	v_add_u32_e32 v0, s45, v59
	v_max_i32_e32 v0, -15, v0
	v_add_u32_e32 v0, 15, v0
	v_min_u32_e32 v0, 30, v0
	v_lshl_add_u32 v0, v0, 2, s44
	v_subrev_u32_e32 v0, s43, v0
	v_add_u32_e32 v73, s68, v0
	v_add_u32_e32 v0, s45, v60
	v_max_i32_e32 v0, -15, v0
	v_add_u32_e32 v0, 15, v0
	v_min_u32_e32 v0, 30, v0
	v_lshl_add_u32 v0, v0, 2, s44
	v_subrev_u32_e32 v0, s43, v0
	v_add_u32_e32 v74, s68, v0
	v_add_u32_e32 v0, s45, v61
	v_max_i32_e32 v0, -15, v0
	v_add_u32_e32 v0, 15, v0
	v_min_u32_e32 v0, 30, v0
	v_lshl_add_u32 v0, v0, 2, s44
	v_subrev_u32_e32 v0, s43, v0
	v_add_u32_e32 v75, s68, v0
	v_add_u32_e32 v0, s45, v54
	v_max_i32_e32 v0, -15, v0
	v_add_u32_e32 v0, 15, v0
	v_min_u32_e32 v0, 30, v0
	s_and_b64 s[12:13], exec, s[38:39]
	v_lshl_add_u32 v0, v0, 2, s44
	s_cselect_b32 s58, 4, 12
	v_sub_u32_e32 v2, v2, v45
	v_subrev_u32_e32 v0, s43, v0
	s_lshl_b32 s42, s42, 6
	v_cmp_gt_u32_e64 s[12:13], 16, v1
	s_mov_b32 s69, 2
	v_cmp_gt_u32_e64 s[16:17], 16, v2
	s_mul_i32 s70, s45, 0x120
	v_add_u32_e32 v76, s68, v0
	s_add_i32 s71, s42, 0x80
	v_mov_b32_e32 v77, 0
	v_mov_b32_e32 v79, 0xf149f2ca
	s_mov_b32 s76, 0
	s_mov_b32 s80, 0
	s_mov_b32 s81, 2
	s_waitcnt vmcnt(0)
	v_readlane_b32 s92, v253, 22
	v_readlane_b32 s93, v253, 23
	v_readlane_b32 s94, v253, 24
	v_readlane_b32 s95, v253, 25
	v_mov_b32_e32 v210, 0xf149f2ca
	s_nop 4

; #define LAS __attribute__((address_space(3)))
; __device__ __forceinline__ f32x4 zero4v() { f32x4 z = (f32x4){0.f, 0.f, 0.f, 0.f}; asm volatile("" : "+v"(z)); return z; }
; __device__ __forceinline__ void na_unit(const Frame& F, int l, int gi, int hp) {
;     ...
;         if (p + 2 < np) NA_DMA(p + 2, sn2);
;         const LAS unsigned char* kb = F.lds + NA_K_OFF + sc * NA_KBUF;
;         const LAS unsigned char* vb = F.lds + NA_V_OFF + sc * NA_VBUF;
;         const bool win = lat && p < 8;
;         const int ntl = win ? 1 : 2;
;         for (int tl = 0; tl < ntl; ++tl) {
;             const int kbase = win ? c0 : tl * 32;
;             f32x4 s[2];
; #pragma unroll
;             for (int ks = 0; ks < 2; ++ks) {
;                 s[ks] = zero4v();
; #pragma unroll
;                 for (int kk = 0; kk < 2; ++kk) {
;                     const bf16x8 kf = *(const LAS bf16x8*)(kb + krd + (kbase + ks * 16) * NA_KSTR + kk * 64);
;                     s[ks] = __builtin_amdgcn_mfma_f32_16x16x32_bf16(kf, Qf[kk], s[ks], 0, 0, 0);
;                 }
;             }
;             if (win) {
;                 const int dr = (r0 + p) - gi + 7;
; #pragma unroll
;                 for (int ks = 0; ks < 2; ++ks)
; #pragma unroll
;                     for (int j = 0; j < 4; ++j) {
;                         const int cc = c0 + 16 * ks + 4 * g + j, rel = cc - cs_;
;                         const bool valid = (rel >= 0) && (rel < 16);
;                         const int bi = min(max(cc - qc + 15, 0), 30);
;                         const float bias = rpb[dr * 31 + bi];
;                         s[ks][j] = valid ? (s[ks][j] * SC + bias) : NEG_BIG;
.LBB0_986:
	s_mul_i32 s45, s81, 0x4800
	s_add_i32 s45, s51, s45
	s_mulk_i32 s44, 0x6a00
	s_mov_b32 m0, s45
	s_add_i32 s47, s45, 0xd800
	s_andn2_b64 vcc, exec, s[30:31]
	s_nop 2
	buffer_load_dwordx4 v63, s[92:95], s44 offen lds
	s_mov_b32 m0, s47
	s_nop 0
	buffer_load_dwordx4 v64, s[92:95], s44 offen lds
	s_add_i32 m0, s45, 0x2000
	s_nop 0
	buffer_load_dwordx4 v65, s[92:95], s44 offen lds
	s_add_i32 m0, s45, 0xf800
	s_nop 0
	buffer_load_dwordx4 v66, s[92:95], s44 offen lds
	s_cbranch_vccnz .LBB0_988
	s_addk_i32 s47, 0x4000
	s_add_i32 m0, s45, 0x4000
	s_nop 4
	buffer_load_dwordx4 v67, s[92:95], s44 offen lds
	s_mov_b32 m0, s47
	s_nop 0
	buffer_load_dwordx4 v68, s[92:95], s44 offen lds
.LBB0_988:
.LBB0_989:
	s_cmp_gt_u32 s46, 7
	s_cselect_b64 s[44:45], -1, 0
	s_or_b64 s[44:45], s[38:39], s[44:45]
	s_mul_i32 s91, s80, 0x4800
	s_and_b64 vcc, s[44:45], exec
	v_add_u32_e32 v78, s91, v47
	s_cselect_b32 s89, 0, s70
	v_add_u32_e32 v36, s89, v78
	ds_read_b128 v[4:7], v36
	ds_read_b128 v[156:159], v36 offset:4608
	ds_read_b128 v[152:155], v36 offset:64
	ds_read_b128 v[160:163], v36 offset:4672
	v_add_u32_e32 v211, s91, v50
	v_add_u32_e32 v211, s89, v211
	ds_read_b64_tr_b16 v[230:231], v211 offset:55296
	ds_read_b64_tr_b16 v[232:233], v211 offset:59904
	ds_read_b64_tr_b16 v[234:235], v211 offset:55360
	ds_read_b64_tr_b16 v[236:237], v211 offset:59968
	ds_read_b64_tr_b16 v[238:239], v211 offset:55328
	ds_read_b64_tr_b16 v[240:241], v211 offset:59936
	ds_read_b64_tr_b16 v[242:243], v211 offset:55392
	ds_read_b64_tr_b16 v[244:245], v211 offset:60000
	s_mov_b64 s[46:47], -1
	s_cbranch_vccnz .Lmy_na_nobias
	v_add_u32_e32 v202, s76, v76
	v_add_u32_e32 v203, s76, v75
	v_add_u32_e32 v204, s76, v74
	v_add_u32_e32 v205, s76, v73
	v_add_u32_e32 v206, s76, v72
	v_add_u32_e32 v207, s76, v71
	v_add_u32_e32 v208, s76, v70
	v_add_u32_e32 v209, s76, v69
	ds_read_b32 v184, v202
	ds_read_b32 v185, v203
	ds_read_b32 v186, v204
	ds_read_b32 v187, v205
	ds_read_b32 v188, v206
	ds_read_b32 v189, v207
	ds_read_b32 v190, v208
	ds_read_b32 v191, v209
.Lmy_na_nobias:
	s_waitcnt lgkmcnt(11)
	v_mfma_f32_16x16x32_bf16 v[0:3], v[4:7], v[8:11], v[132:135]
	s_waitcnt lgkmcnt(10)
	v_mfma_f32_16x16x32_bf16 v[164:167], v[156:159], v[8:11], v[132:135]
	s_waitcnt lgkmcnt(9)
	v_mfma_f32_16x16x32_bf16 v[32:35], v[152:155], v[12:15], v[0:3]
	s_waitcnt lgkmcnt(8)
	v_mfma_f32_16x16x32_bf16 v[36:39], v[160:163], v[12:15], v[164:167]
	s_cbranch_vccnz .LBB0_1007
	s_waitcnt lgkmcnt(0)
	s_nop 0
	s_nop 5
	v_fmac_f32_e32 v184, 0x3e38aa3b, v32
	v_fmac_f32_e32 v185, 0x3e38aa3b, v33
	v_fmac_f32_e32 v186, 0x3e38aa3b, v34
	v_fmac_f32_e32 v187, 0x3e38aa3b, v35
	v_fmac_f32_e32 v188, 0x3e38aa3b, v36
	v_fmac_f32_e32 v189, 0x3e38aa3b, v37
	v_fmac_f32_e32 v190, 0x3e38aa3b, v38
	v_fmac_f32_e32 v191, 0x3e38aa3b, v39
	v_cndmask_b32_e64 v0, v210, v184, s[12:13]
	v_cndmask_b32_e64 v1, v210, v185, s[14:15]
	v_cndmask_b32_e64 v2, v210, v186, s[16:17]
	v_cndmask_b32_e64 v3, v210, v187, s[18:19]
	v_cndmask_b32_e64 v4, v210, v188, s[20:21]
	v_cndmask_b32_e64 v5, v210, v189, s[22:23]
	v_cndmask_b32_e64 v6, v210, v190, s[24:25]
	v_cndmask_b32_e64 v7, v210, v191, s[26:27]
	s_mov_b64 s[46:47], 0
